# adds relaxed store-drain wait at GEMM unit heads, removal of three artifact vmcnt(0) in GEMM prologues, batched w_down fix-up loads/copies, coalesced softmax P stores
# speedup vs baseline: 1.0260x; 1.0038x over previous
.LBB0_199:
	s_add_i32 m0, s41, 0x18000
	v_lshl_add_u64 v[8:9], v[8:9], 0, s[46:47]
	s_waitcnt vmcnt(2)
	s_barrier
	global_load_lds_dwordx4 v[8:9], off
	v_lshl_add_u64 v[8:9], v[10:11], 0, s[46:47]
	s_add_i32 m0, s41, 0x1a000
	s_add_i32 s45, s41, 0x8000
	global_load_lds_dwordx4 v[8:9], off
	v_lshl_add_u64 v[8:9], v[14:15], 0, s[46:47]
	s_mov_b32 m0, s45
	s_add_i32 s48, s41, 0xa000
	global_load_lds_dwordx4 v[8:9], off
	v_lshl_add_u64 v[8:9], v[12:13], 0, s[46:47]
	s_mov_b32 m0, s48
	v_and_b32_e32 v146, 15, v16
	global_load_lds_dwordx4 v[8:9], off
	v_lshl_add_u64 v[8:9], v[4:5], 0, s[72:73]
	s_add_i32 m0, s41, 0x1c000
	v_lshl_add_u64 v[10:11], v[8:9], 0, v[2:3]
	global_load_lds_dwordx4 v[10:11], off
	v_lshl_add_u64 v[8:9], v[8:9], 0, v[0:1]
	s_add_i32 m0, s41, 0x1e000
	v_bfe_u32 v147, v16, 4, 2
	global_load_lds_dwordx4 v[8:9], off
	v_lshlrev_b32_e32 v8, 6, v146
	v_lshlrev_b32_e32 v9, 2, v16
	s_and_b32 s49, s5, 3
	v_lshl_or_b32 v8, v147, 4, v8
	s_lshl_b32 s5, s31, 13
	v_and_b32_e32 v9, 32, v9
	v_bitop3_b32 v10, v8, s5, v9 bitop3:0xde
	s_lshl_b32 s5, s49, 12
	v_bitop3_b32 v148, v8, s5, v9 bitop3:0xde
	v_lshlrev_b32_e32 v8, 14, v20
	v_and_b32_e32 v8, 0xffff8000, v8
	v_lshl_add_u32 v8, v21, 11, v8
	v_and_b32_e32 v9, 1, v20
	v_lshl_or_b32 v8, v9, 6, v8
	v_lshl_add_u32 v132, v22, 1, v8
	v_lshlrev_b32_e32 v8, 14, v17
	s_cmpk_lt_u32 s4, 0x100
	v_and_b32_e32 v8, 0xffff8000, v8
	s_waitcnt vmcnt(6)
	s_cselect_b64 s[12:13], -1, 0
	s_lshl_b64 s[4:5], s[20:21], 23
	v_lshl_add_u32 v8, v18, 11, v8
	v_and_b32_e32 v9, 1, v17
	s_add_u32 s50, s8, s4
	v_lshl_or_b32 v8, v9, 6, v8
	s_addc_u32 s51, s9, s5
	v_mov_b32_e32 v133, v3
	v_lshl_add_u32 v134, v19, 1, v8
	v_mov_b32_e32 v135, v3
	s_mov_b32 s52, 0
	v_add_u32_e32 v149, 0, v10
	s_barrier
	s_branch .LBB0_202

.LBB0_369:
	s_ashr_i32 s35, s34, 31
	s_lshl_b64 s[6:7], s[34:35], 19
	s_add_u32 s38, s45, s6
	s_addc_u32 s39, s48, s7
	s_and_b64 s[6:7], s[4:5], exec
	s_cselect_b32 s1, s39, s9
	s_cselect_b32 s3, s38, s8
	s_ashr_i32 s41, s40, 31
	s_lshl_b64 s[6:7], s[40:41], 19
	s_add_u32 s18, s49, s6
	s_addc_u32 s19, s54, s7
	s_and_b64 s[6:7], s[4:5], exec
	s_cselect_b32 s12, s19, s11
	s_cselect_b32 s13, s18, s10
	s_add_u32 s6, s8, 0x40080
	s_addc_u32 s7, s9, 0
	s_add_u32 s14, s10, 0x100
	v_mov_b32_e32 v4, 0
	s_addc_u32 s15, s11, 0
	s_mov_b32 s21, -2
	v_mov_b32_e32 v5, v4
	v_mov_b32_e32 v6, v4
	v_mov_b32_e32 v7, v4
	v_mov_b32_e32 v40, v4
	v_mov_b32_e32 v41, v4
	v_mov_b32_e32 v42, v4
	v_mov_b32_e32 v43, v4
	v_mov_b32_e32 v8, v4
	v_mov_b32_e32 v9, v4
	v_mov_b32_e32 v10, v4
	v_mov_b32_e32 v11, v4
	v_mov_b32_e32 v44, v4
	v_mov_b32_e32 v45, v4
	v_mov_b32_e32 v46, v4
	v_mov_b32_e32 v47, v4
	v_mov_b32_e32 v12, v4
	v_mov_b32_e32 v13, v4
	v_mov_b32_e32 v14, v4
	v_mov_b32_e32 v15, v4
	v_mov_b32_e32 v48, v4
	v_mov_b32_e32 v49, v4
	v_mov_b32_e32 v50, v4
	v_mov_b32_e32 v51, v4
	v_mov_b32_e32 v16, v4
	v_mov_b32_e32 v17, v4
	v_mov_b32_e32 v18, v4
	v_mov_b32_e32 v19, v4
	v_mov_b32_e32 v52, v4
	v_mov_b32_e32 v53, v4
	v_mov_b32_e32 v54, v4
	v_mov_b32_e32 v55, v4
	v_mov_b32_e32 v36, v4
	v_mov_b32_e32 v37, v4
	v_mov_b32_e32 v38, v4
	v_mov_b32_e32 v39, v4
	v_mov_b32_e32 v32, v4
	v_mov_b32_e32 v33, v4
	v_mov_b32_e32 v34, v4
	v_mov_b32_e32 v35, v4
	v_mov_b32_e32 v20, v4
	v_mov_b32_e32 v21, v4
	v_mov_b32_e32 v22, v4
	v_mov_b32_e32 v23, v4
	v_mov_b32_e32 v56, v4
	v_mov_b32_e32 v57, v4
	v_mov_b32_e32 v58, v4
	v_mov_b32_e32 v59, v4
	v_mov_b32_e32 v24, v4
	v_mov_b32_e32 v25, v4
	v_mov_b32_e32 v26, v4
	v_mov_b32_e32 v27, v4
	v_mov_b32_e32 v60, v4
	v_mov_b32_e32 v61, v4
	v_mov_b32_e32 v62, v4
	v_mov_b32_e32 v63, v4
	v_mov_b32_e32 v28, v4
	v_mov_b32_e32 v29, v4
	v_mov_b32_e32 v30, v4
	v_mov_b32_e32 v31, v4
	v_mov_b32_e32 v64, v4
	v_mov_b32_e32 v65, v4
	v_mov_b32_e32 v66, v4
	v_mov_b32_e32 v67, v4
	s_waitcnt vmcnt(4)
	v_mov_b32_e32 v68, v4
	v_mov_b32_e32 v69, v4
	v_mov_b32_e32 v70, v4
	v_mov_b32_e32 v71, v4
	v_mov_b32_e32 v116, v4
	v_mov_b32_e32 v117, v4
	v_mov_b32_e32 v118, v4
	v_mov_b32_e32 v119, v4
	v_mov_b32_e32 v72, v4
	v_mov_b32_e32 v73, v4
	v_mov_b32_e32 v74, v4
	v_mov_b32_e32 v75, v4
	v_mov_b32_e32 v120, v4
	v_mov_b32_e32 v121, v4
	v_mov_b32_e32 v122, v4
	v_mov_b32_e32 v123, v4
	v_mov_b32_e32 v76, v4
	v_mov_b32_e32 v77, v4
	v_mov_b32_e32 v78, v4
	v_mov_b32_e32 v79, v4
	v_mov_b32_e32 v124, v4
	v_mov_b32_e32 v125, v4
	v_mov_b32_e32 v126, v4
	v_mov_b32_e32 v127, v4
	v_mov_b32_e32 v80, v4
	v_mov_b32_e32 v81, v4
	v_mov_b32_e32 v82, v4
	v_mov_b32_e32 v83, v4
	v_mov_b32_e32 v128, v4
	v_mov_b32_e32 v129, v4
	v_mov_b32_e32 v130, v4
	v_mov_b32_e32 v131, v4
	v_mov_b32_e32 v112, v4
	v_mov_b32_e32 v113, v4
	v_mov_b32_e32 v114, v4
	v_mov_b32_e32 v115, v4
	v_mov_b32_e32 v108, v4
	v_mov_b32_e32 v109, v4
	v_mov_b32_e32 v110, v4
	v_mov_b32_e32 v111, v4
	v_mov_b32_e32 v84, v4
	v_mov_b32_e32 v85, v4
	v_mov_b32_e32 v86, v4
	v_mov_b32_e32 v87, v4
	v_mov_b32_e32 v132, v4
	v_mov_b32_e32 v133, v4
	v_mov_b32_e32 v134, v4
	v_mov_b32_e32 v135, v4
	v_mov_b32_e32 v88, v4
	v_mov_b32_e32 v89, v4
	v_mov_b32_e32 v90, v4
	v_mov_b32_e32 v91, v4
	v_mov_b32_e32 v136, v4
	v_mov_b32_e32 v137, v4
	v_mov_b32_e32 v138, v4
	v_mov_b32_e32 v139, v4
	v_mov_b32_e32 v92, v4
	v_mov_b32_e32 v93, v4
	v_mov_b32_e32 v94, v4
	v_mov_b32_e32 v95, v4
	v_mov_b32_e32 v140, v4
	v_mov_b32_e32 v141, v4
	v_mov_b32_e32 v142, v4
	v_mov_b32_e32 v143, v4

.LBB0_530:
	v_ashrrev_i32_e32 v2, 31, v0
	v_lshrrev_b32_e32 v2, 26, v2
	v_lshlrev_b32_e32 v1, 4, v0
	v_add_u32_e32 v2, v0, v2
	v_bfe_i32 v0, v0, 27, 1
	v_lshrrev_b32_e32 v0, 22, v0
	v_add_u32_e32 v0, v1, v0
	v_and_b32_e32 v0, 0xfffffc00, v0
	v_sub_u32_e32 v0, v1, v0
	v_lshrrev_b32_e32 v4, 4, v0
	v_bitop3_b32 v0, v4, v0, 32 bitop3:0x6c
	v_ashrrev_i32_e32 v5, 31, v0
	v_lshrrev_b32_e32 v5, 26, v5
	v_add_u32_e32 v5, v0, v5
	v_ashrrev_i32_e32 v6, 6, v5
	v_and_b32_e32 v5, 0xc0, v5
	v_ashrrev_i32_e32 v2, 6, v2
	v_sub_u32_e32 v0, v0, v5
	v_lshlrev_b32_e32 v4, 3, v2
	v_lshlrev_b32_e32 v2, 5, v2
	v_ashrrev_i16_sdwa v0, v191, sext(v0) dst_sel:DWORD dst_unused:UNUSED_PAD src0_sel:DWORD src1_sel:BYTE_0
	s_add_u32 s28, s78, s2
	v_and_b32_e32 v4, -16, v4
	v_and_b32_e32 v2, 32, v2
	v_bfe_i32 v0, v0, 0, 16
	s_addc_u32 s29, s79, s3
	v_add_u32_e32 v4, v6, v4
	v_and_b32_e32 v6, 3, v6
	s_mov_b32 s3, 0x1fffe0
	v_add_lshl_u32 v2, v2, v0, 1
	v_add_u32_e32 v1, 0x2000, v1
	v_lshlrev_b32_e32 v5, 1, v4
	v_lshrrev_b32_e32 v7, 2, v4
	v_and_or_b32 v6, v4, s3, v6
	v_lshl_add_u32 v0, v4, 11, v2
	v_ashrrev_i32_e32 v4, 31, v1
	v_lshrrev_b32_e32 v4, 22, v4
	v_and_b32_e32 v5, 24, v5
	v_and_b32_e32 v7, 4, v7
	v_add_u32_e32 v4, v1, v4
	v_or3_b32 v5, v6, v7, v5
	v_ashrrev_i32_e32 v4, 10, v4
	v_lshl_add_u32 v2, v5, 11, v2
	v_mul_i32_i24_e32 v5, 0x400, v4
	v_sub_u32_e32 v1, v1, v5
	v_lshrrev_b32_e32 v5, 4, v1
	v_bitop3_b32 v1, v5, v1, 32 bitop3:0x6c
	v_ashrrev_i32_e32 v6, 31, v1
	v_lshrrev_b32_e32 v6, 26, v6
	s_ashr_i32 s2, s9, 6
	v_lshlrev_b32_e32 v5, 3, v4
	v_add_u32_e32 v6, v1, v6
	v_and_b32_e32 v5, -16, v5
	v_ashrrev_i32_e32 v7, 6, v6
	v_and_b32_e32 v6, 0xc0, v6
	s_ashr_i32 s43, s9, 8
	s_lshl_b32 s55, s2, 10
	v_add_u32_e32 v5, v7, v5
	v_sub_u32_e32 v1, v1, v6
	s_add_u32 s44, s70, s0
	v_lshlrev_b32_e32 v4, 5, v4
	v_ashrrev_i16_sdwa v1, v191, sext(v1) dst_sel:DWORD dst_unused:UNUSED_PAD src0_sel:DWORD src1_sel:BYTE_0
	v_lshlrev_b32_e32 v6, 1, v5
	v_lshrrev_b32_e32 v8, 2, v5
	v_and_b32_e32 v7, 3, v7
	s_addc_u32 s45, s71, s1
	s_add_i32 s58, s55, 0
	v_and_b32_e32 v4, 32, v4
	v_bfe_i32 v1, v1, 0, 16
	v_and_b32_e32 v6, 24, v6
	v_and_b32_e32 v8, 4, v8
	v_and_or_b32 v7, v5, s3, v7
	s_add_i32 m0, s58, 0x10000
	v_or3_b32 v6, v7, v8, v6
	v_add_lshl_u32 v1, v4, v1, 1
	global_load_lds_dwordx4 v2, s[44:45]
	s_add_i32 m0, s58, 0x12000
	v_lshl_add_u32 v134, v6, 11, v1
	s_add_u32 s0, s44, 0x40000
	global_load_lds_dwordx4 v134, s[44:45]
	s_addc_u32 s1, s45, 0
	s_add_i32 m0, s58, 0x14000
	s_add_i32 s59, s58, 0x2000
	global_load_lds_dwordx4 v2, s[0:1]
	s_add_i32 m0, s58, 0x16000
	v_lshl_add_u32 v132, v5, 11, v1
	global_load_lds_dwordx4 v134, s[0:1]
	s_mov_b32 m0, s58
	s_add_u32 s0, s28, 0x40000
	global_load_lds_dwordx4 v0, s[28:29]
	s_mov_b32 m0, s59
	s_addc_u32 s1, s29, 0
	s_add_i32 s61, s58, 0x4000
	global_load_lds_dwordx4 v132, s[28:29]
	s_mov_b32 m0, s61
	s_add_i32 s72, s58, 0x6000
	global_load_lds_dwordx4 v0, s[0:1]
	s_mov_b32 m0, s72
	v_mov_b32_e32 v135, v3
	global_load_lds_dwordx4 v132, s[0:1]
	v_mov_b32_e32 v1, v3
	v_mov_b32_e32 v133, v3
	s_cmp_eq_u32 s43, 1
	v_lshl_add_u64 v[10:11], s[44:45], 0, v[2:3]
	v_lshl_add_u64 v[8:9], s[44:45], 0, v[134:135]
	v_lshl_add_u64 v[4:5], s[28:29], 0, v[0:1]
	s_cselect_b64 s[82:83], -1, 0
	s_cmp_lg_u32 s43, 1
	v_lshl_add_u64 v[6:7], s[28:29], 0, v[132:133]
	s_cbranch_scc1 .LBB0_532
	s_barrier

.LBB0_567:
	s_or_b64 exec, exec, s[8:9]
	v_lshl_add_u32 v146, s28, 6, v153
	v_mbcnt_lo_u32_b32 v243, -1, 0
	v_mbcnt_hi_u32_b32 v243, -1, v243
	v_and_b32_e32 v244, 3, v243
	v_lshrrev_b32_e32 v245, 2, v243
	v_lshlrev_b32_e32 v242, 6, v244
	v_lshl_or_b32 v242, v245, 2, v242
	v_lshl_add_u32 v245, s28, 6, v245
	v_lshl_add_u32 v4, v146, 5, 0
	s_waitcnt lgkmcnt(0)
	s_barrier
	v_add_u32_e32 v4, 0x20000, v4
	ds_read_b128 v[8:11], v4
	s_waitcnt lgkmcnt(0)
	ds_read_b128 v[4:7], v4 offset:16
	s_cmp_eq_u32 s24, 2
	s_cselect_b64 s[8:9], -1, 0
	s_cmp_lt_i32 s24, 1
	s_cbranch_scc1 .LBB0_571
	s_cmp_eq_u32 s24, 1
	s_mov_b64 s[28:29], -1
	s_cbranch_scc0 .LBB0_570
	s_mov_b64 s[28:29], 0

.LBB0_576:
	v_sub_f32_e32 v4, v4, v88
	v_mul_f32_e32 v4, 0x3fb8aa3b, v4
	v_sub_f32_e32 v6, v6, v88
	v_exp_f32_e32 v4, v4
	v_mul_f32_e32 v6, 0x3fb8aa3b, v6
	v_exp_f32_e32 v6, v6
	v_mul_f32_e32 v8, v11, v8
	v_fmac_f32_e32 v8, v9, v10
	s_lshl_b32 s28, s51, 11
	s_ashr_i32 s45, s51, 2
	v_fmac_f32_e32 v8, v5, v4
	s_and_b32 s28, s28, 0x1800
	s_lshl_b32 s29, s45, 8
	v_fmac_f32_e32 v8, v7, v6
	s_lshl_b32 s44, s51, 8
	s_add_i32 s51, s28, s29
	v_rcp_f32_e32 v4, v8
	s_and_b64 s[28:29], exec, s[30:31]
	s_cselect_b32 s28, s44, s51
	s_cselect_b32 s51, 0, s45
	v_ashrrev_i32_e32 v5, 5, v146
	v_cmp_eq_u32_e32 vcc, s51, v5
	s_lshl_b32 s29, s24, 5
	s_lshl_b32 s50, s50, 8
	v_mul_f32_e32 v4, v4, v147
	s_or_b64 vcc, s[30:31], vcc
	s_add_i32 s29, s29, s28
	v_cndmask_b32_e32 v8, 0, v4, vcc
	v_add_u32_e32 v4, s50, v245
	v_lshl_add_u32 v88, v244, 3, s29
	v_mad_i64_i32 v[4:5], s[28:29], s34, v4, 0
	v_ashrrev_i32_e32 v89, 31, v88
	v_lshl_add_u64 v[4:5], v[4:5], 1, s[52:53]
	v_lshl_add_u64 v[10:11], v[88:89], 1, v[4:5]
	v_pk_mul_f32 v[6:7], v[130:131], v[8:9] op_sel_hi:[1,0]
	v_pk_mul_f32 v[4:5], v[128:129], v[8:9] op_sel_hi:[1,0]
	v_pk_mul_f32 v[128:129], v[142:143], v[8:9] op_sel_hi:[1,0]
	v_pk_mul_f32 v[130:131], v[136:137], v[8:9] op_sel_hi:[1,0]
	v_cvt_pk_bf16_f32 v4, v4, v5
	v_cvt_pk_bf16_f32 v5, v6, v7
	s_cmp_lt_i32 s24, 1
	v_cvt_pk_bf16_f32 v6, v130, v131
	v_cvt_pk_bf16_f32 v7, v128, v129
	ds_bpermute_b32 v226, v242, v4
	ds_bpermute_b32 v227, v242, v5
	ds_bpermute_b32 v228, v242, v6
	ds_bpermute_b32 v229, v242, v7
	s_nop 1
	v_pk_mul_f32 v[6:7], v[138:139], v[8:9] op_sel_hi:[1,0]
	v_pk_mul_f32 v[4:5], v[126:127], v[8:9] op_sel_hi:[1,0]
	v_pk_mul_f32 v[126:127], v[144:145], v[8:9] op_sel_hi:[1,0]
	v_pk_mul_f32 v[8:9], v[140:141], v[8:9] op_sel_hi:[1,0]
	v_cvt_pk_bf16_f32 v4, v4, v5
	v_cvt_pk_bf16_f32 v5, v6, v7
	s_nop 0
	v_cvt_pk_bf16_f32 v6, v8, v9
	v_cvt_pk_bf16_f32 v7, v126, v127
	v_add_u32_e32 v126, 16, v146
	ds_bpermute_b32 v230, v242, v4
	ds_bpermute_b32 v231, v242, v5
	ds_bpermute_b32 v232, v242, v6
	ds_bpermute_b32 v233, v242, v7
	s_waitcnt lgkmcnt(0)
	global_store_dwordx4 v[10:11], v[226:229], off
	global_store_dwordx4 v[10:11], v[230:233], off offset:256
	s_nop 1
	v_lshl_add_u32 v4, v126, 5, 0
	v_add_u32_e32 v4, 0x20000, v4
	ds_read_b128 v[8:11], v4
	ds_read_b128 v[4:7], v4 offset:16
	s_cbranch_scc1 .LBB0_580
	s_cmp_eq_u32 s24, 1
	s_mov_b64 s[28:29], -1
	s_cbranch_scc0 .LBB0_579
	s_mov_b64 s[28:29], 0

.LBB0_585:
	v_sub_f32_e32 v4, v4, v127
	v_mul_f32_e32 v4, 0x3fb8aa3b, v4
	v_sub_f32_e32 v6, v6, v127
	v_exp_f32_e32 v4, v4
	v_mul_f32_e32 v6, 0x3fb8aa3b, v6
	v_exp_f32_e32 v6, v6
	v_mul_f32_e32 v8, v11, v8
	v_fmac_f32_e32 v8, v9, v10
	v_fmac_f32_e32 v8, v5, v4
	v_fmac_f32_e32 v8, v7, v6
	v_rcp_f32_e32 v4, v8
	v_ashrrev_i32_e32 v5, 5, v126
	v_cmp_eq_u32_e32 vcc, s51, v5
	s_or_b64 vcc, s[30:31], vcc
	v_mul_f32_e32 v4, v4, v128
	v_cndmask_b32_e32 v8, 0, v4, vcc
	v_add_u32_e32 v4, 0x10, v245
	v_add_u32_e32 v4, s50, v4
	v_mad_i64_i32 v[4:5], s[28:29], s34, v4, 0
	v_lshl_add_u64 v[4:5], v[4:5], 1, s[52:53]
	v_lshl_add_u64 v[10:11], v[88:89], 1, v[4:5]
	v_pk_mul_f32 v[6:7], v[114:115], v[8:9] op_sel_hi:[1,0]
	v_pk_mul_f32 v[4:5], v[112:113], v[8:9] op_sel_hi:[1,0]
	v_pk_mul_f32 v[112:113], v[122:123], v[8:9] op_sel_hi:[1,0]
	v_pk_mul_f32 v[114:115], v[116:117], v[8:9] op_sel_hi:[1,0]
	v_cvt_pk_bf16_f32 v4, v4, v5
	v_cvt_pk_bf16_f32 v5, v6, v7
	s_cmp_lt_i32 s24, 1
	v_cvt_pk_bf16_f32 v6, v114, v115
	v_cvt_pk_bf16_f32 v7, v112, v113
	ds_bpermute_b32 v226, v242, v4
	ds_bpermute_b32 v227, v242, v5
	ds_bpermute_b32 v228, v242, v6
	ds_bpermute_b32 v229, v242, v7
	s_nop 1
	v_pk_mul_f32 v[6:7], v[118:119], v[8:9] op_sel_hi:[1,0]
	v_pk_mul_f32 v[4:5], v[110:111], v[8:9] op_sel_hi:[1,0]
	v_pk_mul_f32 v[110:111], v[124:125], v[8:9] op_sel_hi:[1,0]
	v_pk_mul_f32 v[8:9], v[120:121], v[8:9] op_sel_hi:[1,0]
	v_cvt_pk_bf16_f32 v4, v4, v5
	v_cvt_pk_bf16_f32 v5, v6, v7
	s_nop 0
	v_cvt_pk_bf16_f32 v6, v8, v9
	v_cvt_pk_bf16_f32 v7, v110, v111
	v_add_u32_e32 v110, 32, v146
	ds_bpermute_b32 v230, v242, v4
	ds_bpermute_b32 v231, v242, v5
	ds_bpermute_b32 v232, v242, v6
	ds_bpermute_b32 v233, v242, v7
	s_waitcnt lgkmcnt(0)
	global_store_dwordx4 v[10:11], v[226:229], off
	global_store_dwordx4 v[10:11], v[230:233], off offset:256
	s_nop 1
	v_lshl_add_u32 v4, v110, 5, 0
	v_add_u32_e32 v4, 0x20000, v4
	ds_read_b128 v[8:11], v4
	ds_read_b128 v[4:7], v4 offset:16
	s_cbranch_scc1 .LBB0_589
	s_cmp_eq_u32 s24, 1
	s_mov_b64 s[28:29], -1
	s_cbranch_scc0 .LBB0_588
	s_mov_b64 s[28:29], 0

.LBB0_594:
	v_sub_f32_e32 v4, v4, v111
	v_mul_f32_e32 v4, 0x3fb8aa3b, v4
	v_sub_f32_e32 v6, v6, v111
	v_exp_f32_e32 v4, v4
	v_mul_f32_e32 v6, 0x3fb8aa3b, v6
	v_exp_f32_e32 v6, v6
	v_mul_f32_e32 v8, v11, v8
	v_fmac_f32_e32 v8, v9, v10
	v_fmac_f32_e32 v8, v5, v4
	v_fmac_f32_e32 v8, v7, v6
	v_rcp_f32_e32 v4, v8
	v_ashrrev_i32_e32 v5, 5, v110
	v_cmp_eq_u32_e32 vcc, s51, v5
	s_or_b64 vcc, s[30:31], vcc
	v_mul_f32_e32 v4, v4, v112
	v_cndmask_b32_e32 v8, 0, v4, vcc
	v_add_u32_e32 v4, 0x20, v245
	v_add_u32_e32 v4, s50, v4
	v_mad_i64_i32 v[4:5], s[28:29], s34, v4, 0
	v_lshl_add_u64 v[4:5], v[4:5], 1, s[52:53]
	v_lshl_add_u64 v[10:11], v[88:89], 1, v[4:5]
	v_pk_mul_f32 v[6:7], v[98:99], v[8:9] op_sel_hi:[1,0]
	v_pk_mul_f32 v[4:5], v[96:97], v[8:9] op_sel_hi:[1,0]
	v_pk_mul_f32 v[96:97], v[106:107], v[8:9] op_sel_hi:[1,0]
	v_pk_mul_f32 v[98:99], v[100:101], v[8:9] op_sel_hi:[1,0]
	v_cvt_pk_bf16_f32 v4, v4, v5
	v_cvt_pk_bf16_f32 v5, v6, v7
	s_cmp_lt_i32 s24, 1
	v_cvt_pk_bf16_f32 v6, v98, v99
	v_cvt_pk_bf16_f32 v7, v96, v97
	ds_bpermute_b32 v226, v242, v4
	ds_bpermute_b32 v227, v242, v5
	ds_bpermute_b32 v228, v242, v6
	ds_bpermute_b32 v229, v242, v7
	s_nop 1
	v_pk_mul_f32 v[6:7], v[102:103], v[8:9] op_sel_hi:[1,0]
	v_pk_mul_f32 v[4:5], v[94:95], v[8:9] op_sel_hi:[1,0]
	v_pk_mul_f32 v[94:95], v[108:109], v[8:9] op_sel_hi:[1,0]
	v_pk_mul_f32 v[8:9], v[104:105], v[8:9] op_sel_hi:[1,0]
	v_cvt_pk_bf16_f32 v4, v4, v5
	v_cvt_pk_bf16_f32 v5, v6, v7
	s_nop 0
	v_cvt_pk_bf16_f32 v6, v8, v9
	v_cvt_pk_bf16_f32 v7, v94, v95
	v_add_u32_e32 v94, 48, v146
	ds_bpermute_b32 v230, v242, v4
	ds_bpermute_b32 v231, v242, v5
	ds_bpermute_b32 v232, v242, v6
	ds_bpermute_b32 v233, v242, v7
	s_waitcnt lgkmcnt(0)
	global_store_dwordx4 v[10:11], v[226:229], off
	global_store_dwordx4 v[10:11], v[230:233], off offset:256
	s_nop 1
	v_lshl_add_u32 v4, v94, 5, 0
	v_add_u32_e32 v4, 0x20000, v4
	ds_read_b128 v[8:11], v4
	ds_read_b128 v[4:7], v4 offset:16
	s_cbranch_scc1 .LBB0_598
	s_cmp_eq_u32 s24, 1
	s_mov_b64 s[28:29], -1
	s_cbranch_scc0 .LBB0_597
	s_mov_b64 s[28:29], 0

.LBB0_603:
	v_sub_f32_e32 v4, v4, v95
	v_mul_f32_e32 v4, 0x3fb8aa3b, v4
	v_sub_f32_e32 v6, v6, v95
	v_exp_f32_e32 v4, v4
	v_mul_f32_e32 v6, 0x3fb8aa3b, v6
	v_exp_f32_e32 v6, v6
	v_mul_f32_e32 v8, v11, v8
	v_fmac_f32_e32 v8, v9, v10
	v_fmac_f32_e32 v8, v5, v4
	v_fmac_f32_e32 v8, v7, v6
	v_rcp_f32_e32 v4, v8
	v_ashrrev_i32_e32 v5, 5, v94
	v_cmp_eq_u32_e32 vcc, s51, v5
	s_or_b64 vcc, s[30:31], vcc
	v_mul_f32_e32 v4, v4, v96
	v_cndmask_b32_e32 v8, 0, v4, vcc
	v_add_u32_e32 v4, 0x30, v245
	v_add_u32_e32 v4, s50, v4
	v_mad_i64_i32 v[4:5], s[28:29], s34, v4, 0
	v_lshl_add_u64 v[4:5], v[4:5], 1, s[52:53]
	v_lshl_add_u64 v[10:11], v[88:89], 1, v[4:5]
	v_pk_mul_f32 v[6:7], v[82:83], v[8:9] op_sel_hi:[1,0]
	v_pk_mul_f32 v[4:5], v[80:81], v[8:9] op_sel_hi:[1,0]
	v_pk_mul_f32 v[80:81], v[90:91], v[8:9] op_sel_hi:[1,0]
	v_pk_mul_f32 v[82:83], v[84:85], v[8:9] op_sel_hi:[1,0]
	v_cvt_pk_bf16_f32 v4, v4, v5
	v_cvt_pk_bf16_f32 v5, v6, v7
	s_cmp_lt_i32 s24, 1
	v_cvt_pk_bf16_f32 v6, v82, v83
	v_cvt_pk_bf16_f32 v7, v80, v81
	ds_bpermute_b32 v226, v242, v4
	ds_bpermute_b32 v227, v242, v5
	ds_bpermute_b32 v228, v242, v6
	ds_bpermute_b32 v229, v242, v7
	s_nop 1
	v_pk_mul_f32 v[6:7], v[78:79], v[8:9] op_sel_hi:[1,0]
	v_pk_mul_f32 v[4:5], v[76:77], v[8:9] op_sel_hi:[1,0]
	v_pk_mul_f32 v[76:77], v[92:93], v[8:9] op_sel_hi:[1,0]
	v_pk_mul_f32 v[8:9], v[86:87], v[8:9] op_sel_hi:[1,0]
	v_cvt_pk_bf16_f32 v4, v4, v5
	v_cvt_pk_bf16_f32 v5, v6, v7
	s_nop 0
	v_cvt_pk_bf16_f32 v6, v8, v9
	v_cvt_pk_bf16_f32 v7, v76, v77
	v_add_u32_e32 v76, 0x80, v146
	ds_bpermute_b32 v230, v242, v4
	ds_bpermute_b32 v231, v242, v5
	ds_bpermute_b32 v232, v242, v6
	ds_bpermute_b32 v233, v242, v7
	s_waitcnt lgkmcnt(0)
	global_store_dwordx4 v[10:11], v[226:229], off
	global_store_dwordx4 v[10:11], v[230:233], off offset:256
	s_nop 1
	v_lshl_add_u32 v4, v76, 5, 0
	v_add_u32_e32 v4, 0x20000, v4
	ds_read_b128 v[8:11], v4
	ds_read_b128 v[4:7], v4 offset:16
	s_cbranch_scc1 .LBB0_607
	s_cmp_eq_u32 s24, 1
	s_mov_b64 s[28:29], -1
	s_cbranch_scc0 .LBB0_606
	s_mov_b64 s[28:29], 0

.LBB0_612:
	v_sub_f32_e32 v4, v4, v77
	v_mul_f32_e32 v4, 0x3fb8aa3b, v4
	v_sub_f32_e32 v6, v6, v77
	v_exp_f32_e32 v4, v4
	v_mul_f32_e32 v6, 0x3fb8aa3b, v6
	v_exp_f32_e32 v6, v6
	v_mul_f32_e32 v8, v11, v8
	v_fmac_f32_e32 v8, v9, v10
	v_fmac_f32_e32 v8, v5, v4
	v_fmac_f32_e32 v8, v7, v6
	v_rcp_f32_e32 v4, v8
	v_ashrrev_i32_e32 v5, 5, v76
	v_cmp_eq_u32_e32 vcc, s51, v5
	s_or_b64 vcc, s[30:31], vcc
	v_mul_f32_e32 v4, v4, v78
	v_cndmask_b32_e32 v8, 0, v4, vcc
	v_add_u32_e32 v4, 0x80, v245
	v_add_u32_e32 v4, s50, v4
	v_mad_i64_i32 v[4:5], s[28:29], s34, v4, 0
	v_lshl_add_u64 v[4:5], v[4:5], 1, s[52:53]
	v_lshl_add_u64 v[10:11], v[88:89], 1, v[4:5]
	v_pk_mul_f32 v[6:7], v[66:67], v[8:9] op_sel_hi:[1,0]
	v_pk_mul_f32 v[4:5], v[64:65], v[8:9] op_sel_hi:[1,0]
	v_pk_mul_f32 v[64:65], v[72:73], v[8:9] op_sel_hi:[1,0]
	v_pk_mul_f32 v[66:67], v[68:69], v[8:9] op_sel_hi:[1,0]
	v_cvt_pk_bf16_f32 v4, v4, v5
	v_cvt_pk_bf16_f32 v5, v6, v7
	s_cmp_lt_i32 s24, 1
	v_cvt_pk_bf16_f32 v6, v66, v67
	v_cvt_pk_bf16_f32 v7, v64, v65
	ds_bpermute_b32 v226, v242, v4
	ds_bpermute_b32 v227, v242, v5
	ds_bpermute_b32 v228, v242, v6
	ds_bpermute_b32 v229, v242, v7
	s_nop 1
	v_pk_mul_f32 v[6:7], v[62:63], v[8:9] op_sel_hi:[1,0]
	v_pk_mul_f32 v[4:5], v[60:61], v[8:9] op_sel_hi:[1,0]
	v_pk_mul_f32 v[60:61], v[74:75], v[8:9] op_sel_hi:[1,0]
	v_pk_mul_f32 v[8:9], v[70:71], v[8:9] op_sel_hi:[1,0]
	v_cvt_pk_bf16_f32 v4, v4, v5
	v_cvt_pk_bf16_f32 v5, v6, v7
	s_nop 0
	v_cvt_pk_bf16_f32 v6, v8, v9
	v_cvt_pk_bf16_f32 v7, v60, v61
	v_add_u32_e32 v60, 0x90, v146
	ds_bpermute_b32 v230, v242, v4
	ds_bpermute_b32 v231, v242, v5
	ds_bpermute_b32 v232, v242, v6
	ds_bpermute_b32 v233, v242, v7
	s_waitcnt lgkmcnt(0)
	global_store_dwordx4 v[10:11], v[226:229], off
	global_store_dwordx4 v[10:11], v[230:233], off offset:256
	s_nop 1
	v_lshl_add_u32 v4, v60, 5, 0
	v_add_u32_e32 v4, 0x20000, v4
	ds_read_b128 v[8:11], v4
	ds_read_b128 v[4:7], v4 offset:16
	s_cbranch_scc1 .LBB0_616
	s_cmp_eq_u32 s24, 1
	s_mov_b64 s[28:29], -1
	s_cbranch_scc0 .LBB0_615
	s_mov_b64 s[28:29], 0

.LBB0_621:
	v_sub_f32_e32 v4, v4, v61
	v_mul_f32_e32 v4, 0x3fb8aa3b, v4
	v_sub_f32_e32 v6, v6, v61
	v_exp_f32_e32 v4, v4
	v_mul_f32_e32 v6, 0x3fb8aa3b, v6
	v_exp_f32_e32 v6, v6
	v_mul_f32_e32 v8, v11, v8
	v_fmac_f32_e32 v8, v9, v10
	v_fmac_f32_e32 v8, v5, v4
	v_fmac_f32_e32 v8, v7, v6
	v_rcp_f32_e32 v4, v8
	v_ashrrev_i32_e32 v5, 5, v60
	v_cmp_eq_u32_e32 vcc, s51, v5
	s_or_b64 vcc, s[30:31], vcc
	v_mul_f32_e32 v4, v4, v62
	v_cndmask_b32_e32 v8, 0, v4, vcc
	v_add_u32_e32 v4, 0x90, v245
	v_add_u32_e32 v4, s50, v4
	v_mad_i64_i32 v[4:5], s[28:29], s34, v4, 0
	v_lshl_add_u64 v[4:5], v[4:5], 1, s[52:53]
	v_lshl_add_u64 v[10:11], v[88:89], 1, v[4:5]
	v_pk_mul_f32 v[6:7], v[50:51], v[8:9] op_sel_hi:[1,0]
	v_pk_mul_f32 v[4:5], v[48:49], v[8:9] op_sel_hi:[1,0]
	v_pk_mul_f32 v[48:49], v[56:57], v[8:9] op_sel_hi:[1,0]
	v_pk_mul_f32 v[50:51], v[52:53], v[8:9] op_sel_hi:[1,0]
	v_cvt_pk_bf16_f32 v4, v4, v5
	v_cvt_pk_bf16_f32 v5, v6, v7
	s_cmp_lt_i32 s24, 1
	v_cvt_pk_bf16_f32 v6, v50, v51
	v_cvt_pk_bf16_f32 v7, v48, v49
	ds_bpermute_b32 v226, v242, v4
	ds_bpermute_b32 v227, v242, v5
	ds_bpermute_b32 v228, v242, v6
	ds_bpermute_b32 v229, v242, v7
	s_nop 1
	v_pk_mul_f32 v[6:7], v[46:47], v[8:9] op_sel_hi:[1,0]
	v_pk_mul_f32 v[4:5], v[44:45], v[8:9] op_sel_hi:[1,0]
	v_pk_mul_f32 v[44:45], v[58:59], v[8:9] op_sel_hi:[1,0]
	v_pk_mul_f32 v[8:9], v[54:55], v[8:9] op_sel_hi:[1,0]
	v_cvt_pk_bf16_f32 v4, v4, v5
	v_cvt_pk_bf16_f32 v5, v6, v7
	s_nop 0
	v_cvt_pk_bf16_f32 v6, v8, v9
	v_cvt_pk_bf16_f32 v7, v44, v45
	v_add_u32_e32 v44, 0xa0, v146
	ds_bpermute_b32 v230, v242, v4
	ds_bpermute_b32 v231, v242, v5
	ds_bpermute_b32 v232, v242, v6
	ds_bpermute_b32 v233, v242, v7
	s_waitcnt lgkmcnt(0)
	global_store_dwordx4 v[10:11], v[226:229], off
	global_store_dwordx4 v[10:11], v[230:233], off offset:256
	s_nop 1
	v_lshl_add_u32 v4, v44, 5, 0
	v_add_u32_e32 v4, 0x20000, v4
	ds_read_b128 v[8:11], v4
	ds_read_b128 v[4:7], v4 offset:16
	s_cbranch_scc1 .LBB0_625
	s_cmp_eq_u32 s24, 1
	s_mov_b64 s[28:29], -1
	s_cbranch_scc0 .LBB0_624
	s_mov_b64 s[28:29], 0

.LBB0_630:
	v_sub_f32_e32 v4, v4, v45
	v_mul_f32_e32 v4, 0x3fb8aa3b, v4
	v_sub_f32_e32 v6, v6, v45
	v_exp_f32_e32 v4, v4
	v_mul_f32_e32 v6, 0x3fb8aa3b, v6
	v_exp_f32_e32 v6, v6
	v_mul_f32_e32 v8, v11, v8
	v_fmac_f32_e32 v8, v9, v10
	v_fmac_f32_e32 v8, v5, v4
	v_fmac_f32_e32 v8, v7, v6
	v_rcp_f32_e32 v4, v8
	v_ashrrev_i32_e32 v5, 5, v44
	v_cmp_eq_u32_e32 vcc, s51, v5
	s_or_b64 vcc, s[30:31], vcc
	v_mul_f32_e32 v4, v4, v46
	v_cndmask_b32_e32 v8, 0, v4, vcc
	v_add_u32_e32 v4, 0xa0, v245
	v_add_u32_e32 v4, s50, v4
	v_mad_i64_i32 v[4:5], s[28:29], s34, v4, 0
	v_lshl_add_u64 v[4:5], v[4:5], 1, s[52:53]
	v_lshl_add_u64 v[10:11], v[88:89], 1, v[4:5]
	v_pk_mul_f32 v[4:5], v[32:33], v[8:9] op_sel_hi:[1,0]
	v_pk_mul_f32 v[6:7], v[34:35], v[8:9] op_sel_hi:[1,0]
	v_cvt_pk_bf16_f32 v4, v4, v5
	v_pk_mul_f32 v[32:33], v[40:41], v[8:9] op_sel_hi:[1,0]
	v_cvt_pk_bf16_f32 v5, v6, v7
	v_pk_mul_f32 v[34:35], v[36:37], v[8:9] op_sel_hi:[1,0]
	s_cmp_lt_i32 s24, 1
	v_cvt_pk_bf16_f32 v6, v34, v35
	v_cvt_pk_bf16_f32 v7, v32, v33
	ds_bpermute_b32 v226, v242, v4
	ds_bpermute_b32 v227, v242, v5
	ds_bpermute_b32 v228, v242, v6
	ds_bpermute_b32 v229, v242, v7
	s_nop 1
	v_pk_mul_f32 v[4:5], v[28:29], v[8:9] op_sel_hi:[1,0]
	v_pk_mul_f32 v[6:7], v[30:31], v[8:9] op_sel_hi:[1,0]
	v_cvt_pk_bf16_f32 v4, v4, v5
	v_add_u32_e32 v30, 0xb0, v146
	v_pk_mul_f32 v[28:29], v[42:43], v[8:9] op_sel_hi:[1,0]
	v_pk_mul_f32 v[8:9], v[38:39], v[8:9] op_sel_hi:[1,0]
	v_cvt_pk_bf16_f32 v5, v6, v7
	s_nop 0
	v_cvt_pk_bf16_f32 v6, v8, v9
	v_cvt_pk_bf16_f32 v7, v28, v29
	ds_bpermute_b32 v230, v242, v4
	ds_bpermute_b32 v231, v242, v5
	ds_bpermute_b32 v232, v242, v6
	ds_bpermute_b32 v233, v242, v7
	s_waitcnt lgkmcnt(0)
	global_store_dwordx4 v[10:11], v[226:229], off
	global_store_dwordx4 v[10:11], v[230:233], off offset:256
	s_nop 1
	v_lshl_add_u32 v4, v30, 5, 0
	v_add_u32_e32 v8, 0x20000, v4
	ds_read_b128 v[4:7], v8
	ds_read_b128 v[8:11], v8 offset:16
	s_cbranch_scc1 .LBB0_634
	s_cmp_eq_u32 s24, 1
	s_mov_b64 s[28:29], -1
	s_cbranch_scc0 .LBB0_633
	s_mov_b64 s[28:29], 0

.LBB0_639:
	v_sub_f32_e32 v6, v10, v31
	v_mul_f32_e32 v6, 0x3fb8aa3b, v6
	v_exp_f32_e32 v32, v6
	v_sub_f32_e32 v6, v8, v31
	v_mul_f32_e32 v6, 0x3fb8aa3b, v6
	v_exp_f32_e32 v33, v6
	v_mov_b32_e32 v6, v5
	v_mov_b32_e32 v8, v11
	v_pk_mul_f32 v[6:7], v[6:7], v[28:29]
	v_pk_mul_f32 v[8:9], v[8:9], v[32:33]
	v_add_f32_e32 v5, v6, v7
	v_add_f32_e32 v5, v9, v5
	v_add_f32_e32 v5, v8, v5
	v_rcp_f32_e32 v5, v5
	s_nop 0
	v_mul_f32_e32 v4, v5, v4
	v_ashrrev_i32_e32 v5, 5, v30
	v_cmp_eq_u32_e32 vcc, s51, v5
	s_or_b64 vcc, s[30:31], vcc
	s_nop 0
	v_cndmask_b32_e32 v8, 0, v4, vcc
	v_add_u32_e32 v4, 0xb0, v245
	v_add_u32_e32 v4, s50, v4
	v_mad_i64_i32 v[4:5], s[8:9], s34, v4, 0
	v_lshl_add_u64 v[4:5], v[4:5], 1, s[52:53]
	v_lshl_add_u64 v[10:11], v[88:89], 1, v[4:5]
	v_pk_mul_f32 v[6:7], v[18:19], v[8:9] op_sel_hi:[1,0]
	v_pk_mul_f32 v[4:5], v[16:17], v[8:9] op_sel_hi:[1,0]
	v_pk_mul_f32 v[16:17], v[24:25], v[8:9] op_sel_hi:[1,0]
	v_pk_mul_f32 v[18:19], v[20:21], v[8:9] op_sel_hi:[1,0]
	v_cvt_pk_bf16_f32 v4, v4, v5
	v_cvt_pk_bf16_f32 v5, v6, v7
	s_and_b64 vcc, exec, s[6:7]
	v_cvt_pk_bf16_f32 v6, v18, v19
	v_cvt_pk_bf16_f32 v7, v16, v17
	ds_bpermute_b32 v226, v242, v4
	ds_bpermute_b32 v227, v242, v5
	ds_bpermute_b32 v228, v242, v6
	ds_bpermute_b32 v229, v242, v7
	s_mov_b64 s[6:7], -1
	s_nop 0
	v_pk_mul_f32 v[6:7], v[14:15], v[8:9] op_sel_hi:[1,0]
	v_pk_mul_f32 v[4:5], v[12:13], v[8:9] op_sel_hi:[1,0]
	v_pk_mul_f32 v[12:13], v[26:27], v[8:9] op_sel_hi:[1,0]
	v_pk_mul_f32 v[8:9], v[22:23], v[8:9] op_sel_hi:[1,0]
	v_cvt_pk_bf16_f32 v4, v4, v5
	v_cvt_pk_bf16_f32 v5, v6, v7
	s_nop 0
	v_cvt_pk_bf16_f32 v6, v8, v9
	v_cvt_pk_bf16_f32 v7, v12, v13
	ds_bpermute_b32 v230, v242, v4
	ds_bpermute_b32 v231, v242, v5
	ds_bpermute_b32 v232, v242, v6
	ds_bpermute_b32 v233, v242, v7
	s_waitcnt lgkmcnt(0)
	global_store_dwordx4 v[10:11], v[226:229], off
	global_store_dwordx4 v[10:11], v[230:233], off offset:256
	s_cbranch_vccnz .LBB0_534
	s_andn2_b64 vcc, exec, s[82:83]
	s_cbranch_vccnz .LBB0_533
	s_barrier
	s_branch .LBB0_533

.LBB0_664:
	v_mov_b64_e32 v[4:5], 0x200
	v_cmp_lt_i64_e32 vcc, s[14:15], v[4:5]
	s_mov_b64 s[16:17], -1
	s_cbranch_vccz .LBB0_657
	s_cmpk_lt_i32 s54, 0x80
	s_cselect_b64 s[16:17], -1, 0
	s_and_b64 s[26:27], s[6:7], s[16:17]
	s_and_saveexec_b64 s[16:17], s[26:27]
	s_cbranch_execz .LBB0_656
	global_load_dwordx4 v[4:7], v[80:81], off offset:16
	global_load_dwordx4 v[40:43], v[80:81], off
	global_load_dwordx4 v[12:15], v[82:83], off offset:16
	global_load_dwordx4 v[48:51], v[82:83], off
	global_load_dwordx4 v[8:11], v[84:85], off offset:16
	global_load_dwordx4 v[44:47], v[84:85], off
	s_and_b32 s11, s54, 15
	s_cmp_eq_u32 s11, 0
	s_cbranch_scc1 .LBB0_668
	s_add_i32 s21, s54, -1
	s_mul_hi_i32 s24, s21, 0x5800
	s_mulk_i32 s21, 0x5800
	s_add_u32 s26, s19, s21
	s_addc_u32 s27, s20, s24
	v_lshl_add_u64 v[16:17], v[0:1], 2, s[26:27]
	s_mov_b64 s[28:29], 0x2c00
	v_lshl_add_u64 v[18:19], v[16:17], 0, s[28:29]
	global_load_dwordx4 v[72:75], v[16:17], off
	global_load_dwordx4 v[28:31], v[16:17], off offset:16
	v_add_co_u32_e32 v16, vcc, 0x2000, v16
	s_nop 1
	v_addc_co_u32_e32 v17, vcc, 0, v17, vcc
	global_load_dwordx4 v[52:55], v[16:17], off offset:3072
	s_nop 0
	global_load_dwordx4 v[16:19], v[18:19], off offset:16
	s_branch .LBB0_669
.LBB0_668:
	v_mov_b32_e32 v54, 0
	v_mov_b32_e32 v55, 0
	v_mov_b32_e32 v52, 0
	v_mov_b32_e32 v53, 0
	v_mov_b32_e32 v16, 0
	v_mov_b32_e32 v17, 0
	v_mov_b32_e32 v18, 0
	v_mov_b32_e32 v19, 0
	v_mov_b32_e32 v73, 0
	v_mov_b32_e32 v75, 0
	v_mov_b32_e32 v29, 0
	v_mov_b32_e32 v31, 0
	v_mov_b32_e32 v72, 0
	v_mov_b32_e32 v92, 0
	v_mov_b32_e32 v74, 0
	v_mov_b32_e32 v90, 0
	v_mov_b32_e32 v28, 0
	v_mov_b32_e32 v88, 0
	v_mov_b32_e32 v30, 0
	v_mov_b32_e32 v86, 0
	s_mov_b64 s[28:29], 0x2c00
.LBB0_669:
	v_mad_i64_i32 v[20:21], s[26:27], s54, v238, v[0:1]
	v_lshlrev_b64 v[24:25], 2, v[20:21]
	v_lshl_add_u64 v[26:27], s[2:3], 0, v[24:25]
	global_load_dwordx4 v[20:23], v[26:27], off offset:16
	global_load_dwordx4 v[56:59], v[26:27], off
	v_lshl_add_u64 v[32:33], v[26:27], 0, s[28:29]
	v_add_co_u32_e32 v26, vcc, s91, v26
	v_lshl_add_u64 v[24:25], s[4:5], 0, v[24:25]
	s_nop 0
	v_addc_co_u32_e32 v27, vcc, 0, v27, vcc
	global_load_dwordx4 v[64:67], v[26:27], off offset:3072
	s_nop 0
	global_load_dwordx4 v[32:35], v[32:33], off offset:16
	s_nop 0
	global_load_dwordx4 v[36:39], v[24:25], off offset:16
	global_load_dwordx4 v[68:71], v[24:25], off
	v_lshl_add_u64 v[26:27], v[24:25], 0, s[28:29]
	v_add_co_u32_e32 v24, vcc, s91, v24
	s_nop 1
	v_addc_co_u32_e32 v25, vcc, 0, v25, vcc
	global_load_dwordx4 v[60:63], v[24:25], off offset:3072
	s_nop 0
	global_load_dwordx4 v[24:27], v[26:27], off offset:16
	s_waitcnt vmcnt(0)
	v_mov_b32_e32 v92, v73
	v_mov_b32_e32 v90, v75
	v_mov_b32_e32 v88, v29
	v_mov_b32_e32 v86, v31
	v_mov_b32_e32 v94, v40
	v_mov_b32_e32 v95, v44
	s_lshl_b32 s21, s54, 8
	s_mov_b64 s[30:31], 0x2c00
	v_mov_b32_e32 v89, v21
	v_mov_b32_e32 v73, v56
	v_pk_mul_f32 v[72:73], v[94:95], v[72:73]
	v_mov_b32_e32 v94, v56
	v_fma_f32 v2, v48, v52, v72
	v_add_f32_e32 v2, v2, v73
	v_mul_f32_e32 v29, 0xbfb8aa3b, v2
	v_exp_f32_e32 v29, v29
	v_mov_b32_e32 v72, v48
	v_mov_b32_e32 v73, v44
	v_mov_b32_e32 v95, v64
	v_add_f32_e32 v29, 1.0, v29
	v_rcp_f32_e32 v29, v29
	v_pk_mul_f32 v[72:73], v[72:73], v[94:95]
	v_mov_b32_e32 v44, v41
	v_mov_b32_e32 v93, v57
	v_mul_f32_e32 v2, v2, v29
	v_fma_f32 v29, v40, v52, v72
	v_add_f32_e32 v29, v29, v73
	v_mul_f32_e32 v31, 0xbfb8aa3b, v29
	v_exp_f32_e32 v31, v31
	v_pk_mul_f32 v[72:73], v[44:45], v[92:93]
	v_mov_b32_e32 v44, v49
	v_mov_b32_e32 v64, v57
	v_add_f32_e32 v31, 1.0, v31
	v_rcp_f32_e32 v31, v31
	v_pk_mul_f32 v[44:45], v[44:45], v[64:65]
	v_mov_b32_e32 v75, v58
	v_mov_b32_e32 v52, v50
	v_mul_f32_e32 v29, v29, v31
	s_waitcnt vmcnt(1)
	v_mul_f32_e32 v40, v60, v29
	v_fma_f32 v29, v49, v53, v72
	v_add_f32_e32 v29, v29, v73
	v_mul_f32_e32 v31, 0xbfb8aa3b, v29
	v_exp_f32_e32 v31, v31
	v_mov_b32_e32 v56, v58
	v_mov_b32_e32 v57, v66
	v_mov_b32_e32 v91, v59
	v_add_f32_e32 v31, 1.0, v31
	v_rcp_f32_e32 v31, v31
	v_mov_b32_e32 v66, v59
	v_mov_b32_e32 v87, v23
	v_mul_f32_e32 v2, v68, v2
	v_mul_f32_e32 v29, v29, v31
	v_mul_f32_e32 v48, v69, v29
	v_fma_f32 v29, v41, v53, v44
	v_add_f32_e32 v29, v29, v45
	v_mul_f32_e32 v31, 0xbfb8aa3b, v29
	v_exp_f32_e32 v31, v31
	v_mov_b32_e32 v44, v42
	v_mov_b32_e32 v45, v46
	v_pk_mul_f32 v[44:45], v[44:45], v[74:75]
	v_add_f32_e32 v31, 1.0, v31
	v_rcp_f32_e32 v31, v31
	v_mov_b32_e32 v53, v46
	v_pk_mul_f32 v[52:53], v[52:53], v[56:57]
	v_mov_b32_e32 v46, v43
	v_mul_f32_e32 v29, v29, v31
	v_mul_f32_e32 v41, v61, v29
	v_fma_f32 v29, v50, v54, v44
	v_add_f32_e32 v29, v29, v45
	v_mul_f32_e32 v31, 0xbfb8aa3b, v29
	v_exp_f32_e32 v31, v31
	s_nop 0
	v_add_f32_e32 v31, 1.0, v31
	v_rcp_f32_e32 v31, v31
	s_nop 0
	v_mul_f32_e32 v29, v29, v31
	v_mul_f32_e32 v44, v70, v29
	v_fma_f32 v29, v42, v54, v52
	v_add_f32_e32 v29, v29, v53
	v_mul_f32_e32 v31, 0xbfb8aa3b, v29
	v_exp_f32_e32 v31, v31
	v_pk_mul_f32 v[52:53], v[46:47], v[90:91]
	v_mov_b32_e32 v46, v51
	v_pk_mul_f32 v[46:47], v[46:47], v[66:67]
	v_add_f32_e32 v31, 1.0, v31
	v_rcp_f32_e32 v31, v31
	s_nop 0
	v_mul_f32_e32 v29, v29, v31
	v_mul_f32_e32 v42, v62, v29
	v_fma_f32 v29, v51, v55, v52
	v_add_f32_e32 v29, v29, v53
	v_mul_f32_e32 v31, 0xbfb8aa3b, v29
	v_exp_f32_e32 v31, v31
	s_nop 0
	v_add_f32_e32 v31, 1.0, v31
	v_rcp_f32_e32 v31, v31
	s_nop 0
	v_mul_f32_e32 v29, v29, v31
	v_mul_f32_e32 v45, v71, v29
	v_fma_f32 v29, v43, v55, v46
	v_add_f32_e32 v29, v29, v47
	v_mul_f32_e32 v31, 0xbfb8aa3b, v29
	v_exp_f32_e32 v31, v31
	v_mov_b32_e32 v46, v4
	v_mov_b32_e32 v47, v8
	v_add_f32_e32 v31, 1.0, v31
	v_rcp_f32_e32 v31, v31
	s_nop 0
	v_mul_f32_e32 v29, v29, v31
	v_mul_f32_e32 v43, v63, v29
	v_mov_b32_e32 v29, v20
	v_pk_mul_f32 v[28:29], v[46:47], v[28:29]
	v_mov_b32_e32 v46, v20
	v_fma_f32 v28, v12, v16, v28
	v_add_f32_e32 v28, v28, v29
	v_mul_f32_e32 v29, 0xbfb8aa3b, v28
	v_exp_f32_e32 v29, v29
	v_mov_b32_e32 v47, v32
	v_mov_b32_e32 v32, v21
	v_mov_b32_e32 v31, v22
	v_add_f32_e32 v29, 1.0, v29
	v_rcp_f32_e32 v29, v29
	s_nop 0
	v_mul_f32_e32 v28, v28, v29
	v_mul_f32_e32 v36, v36, v28
	v_mov_b32_e32 v28, v12
	v_mov_b32_e32 v29, v8
	v_pk_mul_f32 v[28:29], v[28:29], v[46:47]
	s_nop 0
	v_fma_f32 v4, v4, v16, v28
	v_add_f32_e32 v4, v4, v29
	v_mul_f32_e32 v8, 0xbfb8aa3b, v4
	v_exp_f32_e32 v8, v8
	s_nop 0
	v_add_f32_e32 v8, 1.0, v8
	v_rcp_f32_e32 v8, v8
	s_nop 0
	v_mul_f32_e32 v4, v4, v8
	v_mov_b32_e32 v8, v5
	v_pk_mul_f32 v[28:29], v[8:9], v[88:89]
	v_mul_f32_e32 v12, v24, v4
	v_fma_f32 v4, v13, v17, v28
	v_add_f32_e32 v4, v4, v29
	v_mul_f32_e32 v8, 0xbfb8aa3b, v4
	v_exp_f32_e32 v8, v8
	s_nop 0
	v_add_f32_e32 v8, 1.0, v8
	v_rcp_f32_e32 v8, v8
	s_nop 0
	v_mul_f32_e32 v4, v4, v8
	v_mov_b32_e32 v8, v13
	v_pk_mul_f32 v[8:9], v[8:9], v[32:33]
	v_mul_f32_e32 v16, v37, v4
	v_fma_f32 v4, v5, v17, v8
	v_add_f32_e32 v4, v4, v9
	v_mul_f32_e32 v5, 0xbfb8aa3b, v4
	v_exp_f32_e32 v5, v5
	v_mov_b32_e32 v8, v22
	v_mov_b32_e32 v9, v34
	v_mov_b32_e32 v34, v23
	v_add_f32_e32 v5, 1.0, v5
	v_rcp_f32_e32 v5, v5
	s_nop 0
	v_mul_f32_e32 v4, v4, v5
	v_mul_f32_e32 v13, v25, v4
	v_mov_b32_e32 v4, v6
	v_mov_b32_e32 v5, v10
	v_pk_mul_f32 v[4:5], v[4:5], v[30:31]
	s_nop 0
	v_fma_f32 v4, v14, v18, v4
	v_add_f32_e32 v4, v4, v5
	v_mul_f32_e32 v5, 0xbfb8aa3b, v4
	v_exp_f32_e32 v5, v5
	s_nop 0
	v_add_f32_e32 v5, 1.0, v5
	v_rcp_f32_e32 v5, v5
	s_nop 0
	v_mul_f32_e32 v4, v4, v5
	v_mul_f32_e32 v17, v38, v4
	v_mov_b32_e32 v4, v14
	v_mov_b32_e32 v5, v10
	v_pk_mul_f32 v[4:5], v[4:5], v[8:9]
	v_mov_b32_e32 v10, v7
	v_fma_f32 v4, v6, v18, v4
	v_add_f32_e32 v4, v4, v5
	v_mul_f32_e32 v5, 0xbfb8aa3b, v4
	v_exp_f32_e32 v5, v5
	v_cvt_pk_bf16_f32 v6, v36, v16
	s_nop 0
	v_add_f32_e32 v5, 1.0, v5
	v_rcp_f32_e32 v5, v5
	s_nop 0
	v_mul_f32_e32 v4, v4, v5
	v_mul_f32_e32 v14, v26, v4
	v_pk_mul_f32 v[4:5], v[10:11], v[86:87]
	v_mov_b32_e32 v10, v15
	v_fma_f32 v4, v15, v19, v4
	v_add_f32_e32 v4, v4, v5
	v_mul_f32_e32 v5, 0xbfb8aa3b, v4
	v_exp_f32_e32 v5, v5
	s_nop 0
	v_add_f32_e32 v5, 1.0, v5
	v_rcp_f32_e32 v5, v5
	s_nop 0
	v_mul_f32_e32 v4, v4, v5
	v_mul_f32_e32 v8, v39, v4
	v_pk_mul_f32 v[4:5], v[10:11], v[34:35]
	s_nop 0
	v_fma_f32 v4, v7, v19, v4
	v_add_f32_e32 v4, v4, v5
	v_mul_f32_e32 v5, 0xbfb8aa3b, v4
	v_exp_f32_e32 v5, v5
	v_cvt_pk_bf16_f32 v7, v17, v8
	v_mad_i64_i32 v[8:9], s[26:27], s21, v238, v[76:77]
	v_add_f32_e32 v5, 1.0, v5
	v_rcp_f32_e32 v5, v5
	s_or_b32 s21, s21, 1
	s_cmp_eq_u32 s11, 15
	v_mul_f32_e32 v4, v4, v5
	v_mul_f32_e32 v10, v27, v4
	v_cvt_pk_bf16_f32 v4, v2, v48
	v_cvt_pk_bf16_f32 v5, v44, v45
	global_store_dwordx4 v[8:9], v[4:7], off
	v_mad_i64_i32 v[8:9], s[26:27], s21, v238, v[76:77]
	s_cselect_b64 s[26:27], -1, 0
	s_cmp_eq_u32 s55, 0
	s_cselect_b64 s[28:29], -1, 0
	s_and_b64 s[26:27], s[26:27], s[28:29]
	s_andn2_b64 vcc, exec, s[26:27]
	v_cvt_pk_bf16_f32 v4, v40, v41
	v_cvt_pk_bf16_f32 v5, v42, v43
	v_cvt_pk_bf16_f32 v6, v12, v13
	v_cvt_pk_bf16_f32 v7, v14, v10
	global_store_dwordx4 v[8:9], v[4:7], off
	s_cbranch_vccnz .LBB0_656
	s_ashr_i32 s11, s54, 4
	s_add_i32 s11, s11, s53
	s_mul_i32 s24, s54, 0x5800
	s_mul_hi_i32 s21, s54, 0x5800
	s_add_u32 s26, s19, s24
	s_addc_u32 s27, s20, s21
	v_lshl_add_u64 v[4:5], v[0:1], 2, s[26:27]
	global_load_dwordx4 v[12:15], v[4:5], off
	global_load_dwordx4 v[16:19], v[4:5], off offset:16
	v_lshl_add_u64 v[10:11], v[4:5], 0, s[30:31]
	v_mov_b32_e32 v6, 0x5800
	v_mad_i64_i32 v[6:7], s[26:27], s11, v6, v[78:79]
	global_load_dwordx4 v[20:23], v[10:11], off
	global_load_dwordx4 v[24:27], v[10:11], off offset:16
	v_add_co_u32_e32 v8, vcc, s91, v6
	s_nop 1
	v_addc_co_u32_e32 v9, vcc, 0, v7, vcc
	s_waitcnt vmcnt(0)
	global_store_dwordx4 v[6:7], v[12:15], off
	global_store_dwordx4 v[6:7], v[16:19], off offset:16
	global_store_dwordx4 v[8:9], v[20:23], off offset:3072
	global_store_dwordx4 v[8:9], v[24:27], off offset:3088
	s_branch .LBB0_656

.LBB0_769:
	s_add_u32 s6, s42, 0x80
	s_addc_u32 s7, s43, 0
	s_add_u32 s52, s52, 0x100
	v_mov_b32_e32 v4, 0
	s_addc_u32 s53, s53, 0
	s_mov_b32 s42, 0
	v_mov_b32_e32 v5, v4
	v_mov_b32_e32 v6, v4
	v_mov_b32_e32 v7, v4
	v_mov_b32_e32 v8, v4
	v_mov_b32_e32 v9, v4
	v_mov_b32_e32 v10, v4
	v_mov_b32_e32 v11, v4
	v_mov_b32_e32 v20, v4
	v_mov_b32_e32 v21, v4
	v_mov_b32_e32 v22, v4
	v_mov_b32_e32 v23, v4
	v_mov_b32_e32 v24, v4
	v_mov_b32_e32 v25, v4
	v_mov_b32_e32 v26, v4
	v_mov_b32_e32 v27, v4
	v_mov_b32_e32 v36, v4
	v_mov_b32_e32 v37, v4
	v_mov_b32_e32 v38, v4
	v_mov_b32_e32 v39, v4
	v_mov_b32_e32 v40, v4
	v_mov_b32_e32 v41, v4
	v_mov_b32_e32 v42, v4
	v_mov_b32_e32 v43, v4
	v_mov_b32_e32 v52, v4
	v_mov_b32_e32 v53, v4
	v_mov_b32_e32 v54, v4
	v_mov_b32_e32 v55, v4
	v_mov_b32_e32 v56, v4
	v_mov_b32_e32 v57, v4
	v_mov_b32_e32 v58, v4
	v_mov_b32_e32 v59, v4
	v_mov_b32_e32 v12, v4
	v_mov_b32_e32 v13, v4
	v_mov_b32_e32 v14, v4
	v_mov_b32_e32 v15, v4
	v_mov_b32_e32 v16, v4
	v_mov_b32_e32 v17, v4
	v_mov_b32_e32 v18, v4
	v_mov_b32_e32 v19, v4
	v_mov_b32_e32 v28, v4
	v_mov_b32_e32 v29, v4
	v_mov_b32_e32 v30, v4
	v_mov_b32_e32 v31, v4
	v_mov_b32_e32 v32, v4
	v_mov_b32_e32 v33, v4
	v_mov_b32_e32 v34, v4
	v_mov_b32_e32 v35, v4
	v_mov_b32_e32 v44, v4
	v_mov_b32_e32 v45, v4
	v_mov_b32_e32 v46, v4
	v_mov_b32_e32 v47, v4
	v_mov_b32_e32 v48, v4
	v_mov_b32_e32 v49, v4
	v_mov_b32_e32 v50, v4
	v_mov_b32_e32 v51, v4
	v_mov_b32_e32 v60, v4
	v_mov_b32_e32 v61, v4
	v_mov_b32_e32 v62, v4
	v_mov_b32_e32 v63, v4
	v_mov_b32_e32 v64, v4
	v_mov_b32_e32 v65, v4
	v_mov_b32_e32 v66, v4
	v_mov_b32_e32 v67, v4
	s_waitcnt vmcnt(4)
	v_mov_b32_e32 v68, v4
	v_mov_b32_e32 v69, v4
	v_mov_b32_e32 v70, v4
	v_mov_b32_e32 v71, v4
	v_mov_b32_e32 v72, v4
	v_mov_b32_e32 v73, v4
	v_mov_b32_e32 v74, v4
	v_mov_b32_e32 v75, v4
	v_mov_b32_e32 v84, v4
	v_mov_b32_e32 v85, v4
	v_mov_b32_e32 v86, v4
	v_mov_b32_e32 v87, v4
	v_mov_b32_e32 v88, v4
	v_mov_b32_e32 v89, v4
	v_mov_b32_e32 v90, v4
	v_mov_b32_e32 v91, v4
	v_mov_b32_e32 v100, v4
	v_mov_b32_e32 v101, v4
	v_mov_b32_e32 v102, v4
	v_mov_b32_e32 v103, v4
	v_mov_b32_e32 v104, v4
	v_mov_b32_e32 v105, v4
	v_mov_b32_e32 v106, v4
	v_mov_b32_e32 v107, v4
	v_mov_b32_e32 v116, v4
	v_mov_b32_e32 v117, v4
	v_mov_b32_e32 v118, v4
	v_mov_b32_e32 v119, v4
	v_mov_b32_e32 v120, v4
	v_mov_b32_e32 v121, v4
	v_mov_b32_e32 v122, v4
	v_mov_b32_e32 v123, v4
	v_mov_b32_e32 v76, v4
	v_mov_b32_e32 v77, v4
	v_mov_b32_e32 v78, v4
	v_mov_b32_e32 v79, v4
	v_mov_b32_e32 v80, v4
	v_mov_b32_e32 v81, v4
	v_mov_b32_e32 v82, v4
	v_mov_b32_e32 v83, v4
	v_mov_b32_e32 v92, v4
	v_mov_b32_e32 v93, v4
	v_mov_b32_e32 v94, v4
	v_mov_b32_e32 v95, v4
	v_mov_b32_e32 v96, v4
	v_mov_b32_e32 v97, v4
	v_mov_b32_e32 v98, v4
	v_mov_b32_e32 v99, v4
	v_mov_b32_e32 v108, v4
	v_mov_b32_e32 v109, v4
	v_mov_b32_e32 v110, v4
	v_mov_b32_e32 v111, v4
	v_mov_b32_e32 v112, v4
	v_mov_b32_e32 v113, v4
	v_mov_b32_e32 v114, v4
	v_mov_b32_e32 v115, v4
	v_mov_b32_e32 v124, v4
	v_mov_b32_e32 v125, v4
	v_mov_b32_e32 v126, v4
	v_mov_b32_e32 v127, v4
	v_mov_b32_e32 v128, v4
	v_mov_b32_e32 v129, v4
	v_mov_b32_e32 v130, v4
	v_mov_b32_e32 v131, v4

.LBB0_922:
	s_andn2_b64 vcc, exec, s[6:7]
	s_cbranch_vccnz .LBB0_964
	v_ashrrev_i32_e32 v2, 31, v0
	v_lshrrev_b32_e32 v2, 26, v2
	v_lshlrev_b32_e32 v1, 4, v0
	v_add_u32_e32 v2, v0, v2
	v_bfe_i32 v0, v0, 27, 1
	v_lshrrev_b32_e32 v0, 22, v0
	v_add_u32_e32 v0, v1, v0
	v_and_b32_e32 v0, 0xfffffc00, v0
	v_sub_u32_e32 v0, v1, v0
	v_lshrrev_b32_e32 v4, 4, v0
	v_bitop3_b32 v0, v4, v0, 32 bitop3:0x6c
	v_ashrrev_i32_e32 v5, 31, v0
	v_ashrrev_i32_e32 v2, 6, v2
	v_lshrrev_b32_e32 v5, 26, v5
	s_waitcnt lgkmcnt(0)
	s_add_u32 s11, s0, s4
	v_lshlrev_b32_e32 v4, 3, v2
	v_add_u32_e32 v5, v0, v5
	v_lshlrev_b32_e32 v2, 5, v2
	s_addc_u32 s19, s1, s5
	v_and_b32_e32 v16, 32, v2
	v_and_b32_e32 v2, 0xc0, v5
	s_add_u32 s2, s0, s2
	v_and_b32_e32 v4, -16, v4
	v_ashrrev_i32_e32 v6, 6, v5
	v_sub_u32_e32 v0, v0, v2
	s_addc_u32 s3, s1, s3
	v_readlane_b32 s4, v254, 37
	v_add_u32_e32 v4, v6, v4
	v_ashrrev_i16_sdwa v0, v191, sext(v0) dst_sel:DWORD dst_unused:UNUSED_PAD src0_sel:DWORD src1_sel:BYTE_0
	s_add_u32 s20, s2, s4
	v_bfe_i32 v17, v0, 0, 16
	v_lshlrev_b32_e32 v0, 1, v4
	v_lshrrev_b32_e32 v5, 2, v4
	v_and_b32_e32 v6, 3, v6
	s_mov_b32 s2, 0x7fffffe0
	v_and_b32_e32 v0, 24, v0
	v_and_b32_e32 v5, 4, v5
	v_and_or_b32 v6, v4, s2, v6
	v_or3_b32 v5, v6, v5, v0
	v_add_u32_e32 v2, v16, v17
	v_mul_lo_u32 v18, v4, s31
	v_mul_lo_u32 v4, v5, s31
	v_add_u32_e32 v1, 0x2000, v1
	v_add_lshl_u32 v0, v2, v18, 1
	v_add_lshl_u32 v2, v4, v2, 1
	v_ashrrev_i32_e32 v4, 31, v1
	v_lshrrev_b32_e32 v4, 22, v4
	v_add_u32_e32 v4, v1, v4
	v_ashrrev_i32_e32 v4, 10, v4
	v_mul_i32_i24_e32 v5, 0x400, v4
	v_sub_u32_e32 v1, v1, v5
	v_lshrrev_b32_e32 v5, 4, v1
	v_bitop3_b32 v1, v5, v1, 32 bitop3:0x6c
	v_ashrrev_i32_e32 v6, 31, v1
	v_lshrrev_b32_e32 v6, 26, v6
	v_lshlrev_b32_e32 v5, 3, v4
	v_add_u32_e32 v6, v1, v6
	s_addc_u32 s21, s3, 0
	s_ashr_i32 s4, s28, 6
	v_and_b32_e32 v5, -16, v5
	v_ashrrev_i32_e32 v7, 6, v6
	s_lshl_b32 s43, s31, 9
	v_add_u32_e32 v5, v7, v5
	v_and_b32_e32 v7, 3, v7
	s_ashr_i32 s44, s28, 8
	s_lshl_b32 s24, s31, 8
	s_lshl_b32 s45, s4, 10
	s_mul_i32 s3, s18, s34
	v_lshlrev_b32_e32 v4, 5, v4
	v_and_or_b32 v7, v5, s2, v7
	s_mul_hi_i32 s2, s18, s34
	s_add_u32 s38, s11, s3
	v_and_b32_e32 v19, 32, v4
	v_and_b32_e32 v4, 0xc0, v6
	s_addc_u32 s39, s19, s2
	s_mul_i32 s3, s30, s43
	v_sub_u32_e32 v1, v1, v4
	v_lshlrev_b32_e32 v4, 1, v5
	v_lshrrev_b32_e32 v6, 2, v5
	s_mul_hi_i32 s2, s30, s43
	s_add_u32 s40, s20, s3
	v_ashrrev_i16_sdwa v1, v191, sext(v1) dst_sel:DWORD dst_unused:UNUSED_PAD src0_sel:DWORD src1_sel:BYTE_0
	v_and_b32_e32 v4, 24, v4
	v_and_b32_e32 v6, 4, v6
	s_addc_u32 s41, s21, s2
	s_add_i32 s48, s45, 0
	v_bfe_i32 v21, v1, 0, 16
	v_or3_b32 v4, v7, v6, v4
	s_add_i32 m0, s48, 0x10000
	v_add_u32_e32 v1, v19, v21
	v_mul_lo_u32 v4, v4, s31
	global_load_lds_dwordx4 v2, s[40:41]
	s_add_i32 m0, s48, 0x12000
	v_add_lshl_u32 v162, v4, v1, 1
	s_add_u32 s2, s40, s24
	global_load_lds_dwordx4 v162, s[40:41]
	s_addc_u32 s3, s41, 0
	s_add_i32 m0, s48, 0x14000
	v_mov_b32_e32 v163, v3
	global_load_lds_dwordx4 v2, s[2:3]
	s_add_i32 m0, s48, 0x16000
	s_add_i32 s49, s48, 0x2000
	v_mul_lo_u32 v22, v5, s31
	v_lshl_add_u64 v[8:9], s[2:3], 0, v[2:3]
	v_lshl_add_u64 v[10:11], s[2:3], 0, v[162:163]
	global_load_lds_dwordx4 v162, s[2:3]
	s_mov_b32 m0, s48
	s_add_u32 s2, s38, s24
	v_add_lshl_u32 v160, v1, v22, 1
	global_load_lds_dwordx4 v0, s[38:39]
	s_mov_b32 m0, s49
	s_addc_u32 s3, s39, 0
	s_add_i32 s52, s48, 0x4000
	global_load_lds_dwordx4 v160, s[38:39]
	s_mov_b32 m0, s52
	s_add_i32 s53, s48, 0x6000
	global_load_lds_dwordx4 v0, s[2:3]
	s_mov_b32 m0, s53
	v_mov_b32_e32 v1, v3
	global_load_lds_dwordx4 v160, s[2:3]
	v_mov_b32_e32 v161, v3
	s_cmp_eq_u32 s44, 1
	v_lshl_add_u64 v[4:5], s[40:41], 0, v[2:3]
	v_lshl_add_u64 v[6:7], s[40:41], 0, v[162:163]
	v_lshl_add_u64 v[12:13], s[38:39], 0, v[0:1]
	v_lshl_add_u64 v[14:15], s[38:39], 0, v[160:161]
	s_cselect_b64 s[2:3], -1, 0
	s_cmp_lg_u32 s44, 1
	s_cbranch_scc1 .LBB0_925
	s_barrier
